# attention epilogue: eight row-per-lane 8-byte stores widened to four 16-byte stores via v_permlane32_swap pairs (strategy 7.3)
# baseline (speedup 1.0000x reference)
.LBB0_943:
	global_load_dword v0, v[130:131], off offset:8
	v_mov_b32_e32 v129, v1
	s_add_i32 s94, s94, s95
	s_cmpk_lt_i32 s94, 0x200
	s_waitcnt vmcnt(0)
	v_div_scale_f32 v2, s[0:1], v244, v244, v0
	v_rcp_f32_e32 v3, v2
	s_nop 0
	v_fma_f32 v4, -v2, v3, 1.0
	v_fmac_f32_e32 v3, v4, v3
	v_div_scale_f32 v4, vcc, v0, v244, v0
	v_mul_f32_e32 v5, v4, v3
	v_fma_f32 v6, -v2, v5, v4
	v_fmac_f32_e32 v5, v6, v3
	v_fma_f32 v2, -v2, v5, v4
	v_div_fmas_f32 v2, v2, v3, v5
	v_div_fixup_f32 v0, v2, v244, v0
	ds_read2st64_b32 v[2:3], v227 offset0:84 offset1:85
	ds_read2st64_b32 v[4:5], v227 offset0:100 offset1:101
	ds_read2st64_b32 v[6:7], v227 offset0:86 offset1:87
	ds_read2st64_b32 v[8:9], v227 offset0:102 offset1:103
	ds_read2st64_b32 v[10:11], v227 offset0:88 offset1:89
	ds_read2st64_b32 v[12:13], v227 offset0:104 offset1:105
	s_waitcnt lgkmcnt(5)
	v_pk_fma_f32 v[2:3], v[32:33], v[0:1], v[2:3] op_sel_hi:[1,0,1]
	s_waitcnt lgkmcnt(4)
	v_pk_fma_f32 v[4:5], v[16:17], v[0:1], v[4:5] op_sel_hi:[1,0,1]
	s_waitcnt lgkmcnt(2)
	v_pk_fma_f32 v[8:9], v[18:19], v[0:1], v[8:9] op_sel_hi:[1,0,1]
	s_waitcnt lgkmcnt(0)
	v_pk_fma_f32 v[12:13], v[20:21], v[0:1], v[12:13] op_sel_hi:[1,0,1]
	ds_read2st64_b32 v[14:15], v227 offset0:90 offset1:91
	ds_read2st64_b32 v[16:17], v227 offset0:106 offset1:107
	ds_read2st64_b32 v[18:19], v227 offset0:92 offset1:93
	ds_read2st64_b32 v[20:21], v227 offset0:108 offset1:109
	v_pk_fma_f32 v[6:7], v[34:35], v[0:1], v[6:7] op_sel_hi:[1,0,1]
	v_pk_fma_f32 v[10:11], v[36:37], v[0:1], v[10:11] op_sel_hi:[1,0,1]
	s_waitcnt lgkmcnt(3)
	v_pk_fma_f32 v[14:15], v[38:39], v[0:1], v[14:15] op_sel_hi:[1,0,1]
	s_waitcnt lgkmcnt(2)
	v_pk_fma_f32 v[16:17], v[22:23], v[0:1], v[16:17] op_sel_hi:[1,0,1]
	s_waitcnt lgkmcnt(0)
	v_pk_fma_f32 v[20:21], v[24:25], v[0:1], v[20:21] op_sel_hi:[1,0,1]
	ds_read2st64_b32 v[22:23], v227 offset0:94 offset1:95
	ds_read2st64_b32 v[24:25], v227 offset0:110 offset1:111
	v_cvt_pk_bf16_f32 v96, v2, v3
	v_cvt_pk_bf16_f32 v97, v6, v7
	v_pk_fma_f32 v[18:19], v[40:41], v[0:1], v[18:19] op_sel_hi:[1,0,1]
	s_waitcnt lgkmcnt(1)
	v_pk_fma_f32 v[22:23], v[42:43], v[0:1], v[22:23] op_sel_hi:[1,0,1]
	s_waitcnt lgkmcnt(0)
	v_pk_fma_f32 v[24:25], v[26:27], v[0:1], v[24:25] op_sel_hi:[1,0,1]
	ds_read2st64_b32 v[26:27], v227 offset0:96 offset1:97
	ds_read2st64_b32 v[32:33], v227 offset0:112 offset1:113
	s_waitcnt lgkmcnt(1)
	v_pk_fma_f32 v[26:27], v[44:45], v[0:1], v[26:27] op_sel_hi:[1,0,1]
	s_waitcnt lgkmcnt(0)
	v_pk_fma_f32 v[28:29], v[28:29], v[0:1], v[32:33] op_sel_hi:[1,0,1]
	ds_read2st64_b32 v[32:33], v227 offset0:98 offset1:99
	ds_read2st64_b32 v[34:35], v227 offset0:114 offset1:115
	s_waitcnt lgkmcnt(1)
	v_pk_fma_f32 v[32:33], v[46:47], v[0:1], v[32:33] op_sel_hi:[1,0,1]
	s_waitcnt lgkmcnt(0)
	v_pk_fma_f32 v[30:31], v[30:31], v[0:1], v[34:35] op_sel_hi:[1,0,1]
	v_lshl_add_u64 v[34:35], s[86:87], 0, v[128:129]
	v_lshl_add_u64 v[34:35], s[88:89], 1, v[34:35]
	v_lshl_add_u64 v[34:35], v[118:119], 1, v[34:35]
	v_and_b32_e32 v2, 32, v202
	v_lshrrev_b32_e32 v2, 2, v2
	v_mov_b32_e32 v3, 0
	v_lshl_add_u64 v[34:35], v[34:35], 0, v[2:3]
	v_cvt_pk_bf16_f32 v98, v10, v11
	v_cvt_pk_bf16_f32 v99, v14, v15
	v_cvt_pk_bf16_f32 v100, v18, v19
	v_cvt_pk_bf16_f32 v101, v22, v23
	v_permlane32_swap_b32_e32 v96, v98
	v_permlane32_swap_b32_e32 v97, v99
	v_cvt_pk_bf16_f32 v102, v26, v27
	v_cvt_pk_bf16_f32 v103, v32, v33
	global_store_dwordx4 v[34:35], v[96:99], off
	v_cvt_pk_bf16_f32 v104, v4, v5
	v_cvt_pk_bf16_f32 v105, v8, v9
	v_permlane32_swap_b32_e32 v100, v102
	v_permlane32_swap_b32_e32 v101, v103
	v_cvt_pk_bf16_f32 v106, v12, v13
	v_cvt_pk_bf16_f32 v107, v16, v17
	global_store_dwordx4 v[34:35], v[100:103], off offset:32
	v_cvt_pk_bf16_f32 v108, v20, v21
	v_cvt_pk_bf16_f32 v109, v24, v25
	v_permlane32_swap_b32_e32 v104, v106
	v_permlane32_swap_b32_e32 v105, v107
	v_cvt_pk_bf16_f32 v110, v28, v29
	v_cvt_pk_bf16_f32 v111, v30, v31
	global_store_dwordx4 v[34:35], v[104:107], off offset:64
	s_nop 1
	v_permlane32_swap_b32_e32 v108, v110
	v_permlane32_swap_b32_e32 v109, v111
	global_store_dwordx4 v[34:35], v[108:111], off offset:96
	s_barrier
	s_cbranch_scc0 .LBB0_1001
